# P0 x->bf16 loop: wave_sum butterfly via DPP/permlane swaps instead of 6 serial ds_bpermute (bit-identical), on top of v45
# baseline (speedup 1.0000x reference)
.LBB0_364:
	s_ashr_i32 s4, s2, 31
	s_lshr_b32 s4, s4, 17
	s_add_i32 s4, s2, s4
	s_and_b32 s4, s4, 0xffff8000
	s_sub_i32 s4, s2, s4
	s_ashr_i32 s5, s4, 31
	s_lshl_b64 s[6:7], s[4:5], 12
	v_lshl_add_u64 v[12:13], v[22:23], 0, s[6:7]
	global_load_dwordx4 v[0:3], v[12:13], off nt
	global_load_dwordx4 v[4:7], v[12:13], off offset:1024 nt
	global_load_dwordx4 v[8:11], v[12:13], off offset:2048 nt
	s_nop 0
	global_load_dwordx4 v[12:15], v[12:13], off offset:3072 nt
	s_lshl_b64 s[10:11], s[4:5], 10
	v_lshl_add_u64 v[16:17], v[24:25], 0, s[10:11]
	global_load_dwordx4 v[16:19], v[16:17], off nt
	s_waitcnt vmcnt(4)
	v_mul_f32_e32 v36, v1, v1
	v_mul_f32_e32 v37, v3, v3
	s_waitcnt vmcnt(3)
	v_mul_f32_e32 v38, v5, v5
	v_mul_f32_e32 v39, v7, v7
	s_waitcnt vmcnt(2)
	v_mul_f32_e32 v40, v9, v9
	v_mul_f32_e32 v41, v11, v11
	v_fmac_f32_e32 v36, v0, v0
	v_fmac_f32_e32 v37, v2, v2
	v_fmac_f32_e32 v38, v4, v4
	v_fmac_f32_e32 v39, v6, v6
	s_waitcnt vmcnt(1)
	v_mul_f32_e32 v42, v13, v13
	v_mul_f32_e32 v43, v15, v15
	v_fmac_f32_e32 v40, v8, v8
	v_fmac_f32_e32 v41, v10, v10
	v_add_f32_e32 v36, v36, v37
	v_add_f32_e32 v37, v38, v39
	v_fmac_f32_e32 v42, v12, v12
	v_fmac_f32_e32 v43, v14, v14
	v_add_f32_e32 v38, v40, v41
	v_add_f32_e32 v36, v36, v37
	v_add_f32_e32 v36, v36, v38
	v_add_f32_e32 v37, v42, v43
	v_add_f32_e32 v36, v36, v37
	s_nop 1
	v_add_f32_dpp v36, v36, v36 quad_perm:[1,0,3,2] row_mask:0xf bank_mask:0xf
	s_nop 1
	v_add_f32_dpp v36, v36, v36 quad_perm:[2,3,0,1] row_mask:0xf bank_mask:0xf
	s_nop 1
	v_mov_b32_dpp v37, v36 row_half_mirror row_mask:0xf bank_mask:0xf
	s_nop 1
	v_add_f32_dpp v36, v37, v36 quad_perm:[3,2,1,0] row_mask:0xf bank_mask:0xf
	s_nop 1
	v_add_f32_dpp v36, v36, v36 row_ror:8 row_mask:0xf bank_mask:0xf
	v_mov_b32_e32 v37, v36
	s_nop 1
	v_permlane16_swap_b32_e32 v37, v36
	v_add_f32_e32 v36, v36, v37
	v_mov_b32_e32 v37, v36
	s_nop 1
	v_permlane32_swap_b32_e32 v37, v36
	s_and_saveexec_b64 s[12:13], vcc
	s_cbranch_execz .LBB0_363
	s_waitcnt lgkmcnt(0)
	v_add_f32_e32 v36, v36, v37
	v_fmamk_f32 v36, v36, 0x3a800000, v20
	v_mul_f32_e32 v37, 0x4b800000, v36
	v_cmp_gt_f32_e64 s[6:7], s15, v36
	s_lshl_b64 s[28:29], s[4:5], 2
	s_add_u32 s28, s9, s28
	v_cndmask_b32_e64 v36, v36, v37, s[6:7]
	v_rsq_f32_e32 v36, v36
	s_addc_u32 s29, s14, s29
	v_mul_f32_e32 v37, 0x45800000, v36
	v_cndmask_b32_e64 v36, v36, v37, s[6:7]
	global_store_dword v21, v36, s[28:29]
	s_branch .LBB0_363
